# speedup vs baseline: 1.0062x; 1.0062x over previous
; #define LAS __attribute__((address_space(3)))
; __global__ void __launch_bounds__(512, 2) fwd_megakernel(Params p) {
;   extern __shared__ __attribute__((aligned(16))) char lds[];
;   cg::grid_group grid = cg::this_grid();
;   unsigned* bar = (unsigned*)(p.ws + OFF_BAR);
;   volatile LAS unsigned* st = (volatile LAS unsigned*)(lds + LDS_BYTES);
;   {
;     const unsigned slot = (unsigned)__builtin_amdgcn_s_getreg((5 << 11) | 4) & 63u;
;     if ((threadIdx.x & 63) == 0) *(volatile __attribute__((address_space(3))) int*)(size_t)(WTBL_OFF + slot * 4) = (int)(threadIdx.x >> 6);
;     if (threadIdx.x == 0) { st[0] = 0u; st[1] = 0u; }
;     __syncthreads();
;   }
_Z14fwd_megakernel6Params:
	v_readfirstlane_b32 s100, v0
	s_nop 3
	s_bfe_u32 s100, s100, 0x40006
	s_cmp_ge_u32 s100, 4
	s_cbranch_scc1 .Lmy_prio_done
	s_setprio 1
